# stack4 plus in-proj gate epilogue: gate bias vectors loaded once per tile instead of per sub-block
# speedup vs baseline: 1.0041x; 1.0040x over previous
; __device__ __forceinline__ float sigmoidf_(float x) { return __builtin_amdgcn_rcpf(1.0f + __builtin_amdgcn_exp2f(-1.4426950408889634f * x)); }
;     __device__ __forceinline__ void operator()(const Acc& acc, const Unit& u, int wr, int wc, int fr, int fq) const {
;     ...
;         const float* gbp = gate_b + (mode == 2 ? (sec - 5) * 1024 + col0 : 0);
; #pragma unroll
;         for (int ai = 0; ai < 2; ++ai)
; #pragma unroll
;             for (int m = 0; m < 4; ++m) { const int row = row0 + ai * HALF + m * 16; bf16_t* rowp = dst + (size_t)row * pitch + col0;
;                 if (mode == 0) rowp = dst + ((size_t)(((row >> 14) * 8 + tl * 2) * SEQ + (row & (SEQ - 1)))) * 128 + wc * 32 + 8 * fq;
; #pragma unroll
;                 for (int bj = 0; bj < 2; ++bj) { f32x4 v0 = acc[ai][bj][m][0], v1 = acc[ai][bj][m][1];
;                     if (mode == 1) { f32x2 a = gelu_pk((f32x2){v0[0], v0[1]}), b = gelu_pk((f32x2){v0[2], v0[3]}), c = gelu_pk((f32x2){v1[0], v1[1]}), d = gelu_pk((f32x2){v1[2], v1[3]});
;                         v0 = (f32x4){a.x, a.y, b.x, b.y}; v1 = (f32x4){c.x, c.y, d.x, d.y}; }
;                     else if (mode == 2) { v0 = v0 + *(const f32x4*)(gbp + bj * HALF); v1 = v1 + *(const f32x4*)(gbp + bj * HALF + 4);
; #pragma unroll
;                         for (int i = 0; i < 4; ++i) { v0[i] = sigmoidf_(v0[i]); v1[i] = sigmoidf_(v1[i]); } }
.LBB0_191:
	s_lshl_b32 s12, s93, 10
	s_addk_i32 s12, 0xec00
	v_add_u32_e32 v140, s12, v140
	v_ashrrev_i32_e32 v141, 31, v140
	s_xor_b64 s[24:25], s[18:19], -1
	v_cndmask_b32_e64 v141, 0, v141, s[44:45]
	v_cndmask_b32_e64 v140, 0, v140, s[44:45]
	v_cndmask_b32_e64 v148, 0, 1, s[44:45]
	v_lshl_add_u64 v[140:141], v[140:141], 2, s[50:51]
	global_load_dwordx4 v[232:235], v[140:141], off
	global_load_dwordx4 v[236:239], v[140:141], off offset:16
	global_load_dwordx4 v[240:243], v[140:141], off offset:512
	global_load_dwordx4 v[244:247], v[140:141], off offset:528
	s_mov_b64 s[18:19], -1
	s_and_b64 vcc, exec, s[24:25]
	v_cmp_ne_u32_e64 s[44:45], 1, v148
	s_cbranch_vccz .LBB0_195
	s_and_b64 vcc, exec, s[44:45]
	v_mov_b32_e32 v149, v123
	v_mov_b32_e32 v148, v122
	v_mov_b32_e32 v161, v121
	v_mov_b32_e32 v160, v120
	v_mov_b32_e32 v159, v127
	v_mov_b32_e32 v158, v126
	v_mov_b32_e32 v157, v125
	v_mov_b32_e32 v156, v124
	s_cbranch_vccnz .LBB0_194
	s_waitcnt vmcnt(0)
	v_mov_b32_e32 v156, v232
	v_mov_b32_e32 v157, v233
	v_mov_b32_e32 v158, v234
	v_mov_b32_e32 v159, v235
	v_mov_b32_e32 v160, v236
	v_mov_b32_e32 v161, v237
	v_mov_b32_e32 v162, v238
	v_mov_b32_e32 v163, v239
	v_pk_add_f32 v[148:149], v[126:127], v[158:159]
	v_pk_add_f32 v[156:157], v[124:125], v[156:157]
	v_pk_add_f32 v[158:159], v[122:123], v[162:163]
	v_pk_add_f32 v[160:161], v[120:121], v[160:161]
	v_mul_f32_e32 v156, 0xbfb8aa3b, v156
	v_mul_f32_e32 v160, 0xbfb8aa3b, v160
	v_mul_f32_e32 v157, 0xbfb8aa3b, v157
	v_mul_f32_e32 v161, 0xbfb8aa3b, v161
	v_mul_f32_e32 v148, 0xbfb8aa3b, v148
	v_mul_f32_e32 v158, 0xbfb8aa3b, v158
	v_mul_f32_e32 v149, 0xbfb8aa3b, v149
	v_mul_f32_e32 v159, 0xbfb8aa3b, v159
	v_exp_f32_e32 v156, v156
	v_exp_f32_e32 v160, v160
	v_exp_f32_e32 v157, v157
	v_exp_f32_e32 v161, v161
	v_exp_f32_e32 v148, v148
	v_exp_f32_e32 v158, v158
	v_exp_f32_e32 v149, v149
	v_exp_f32_e32 v159, v159
	v_add_f32_e32 v156, 1.0, v156
	v_add_f32_e32 v160, 1.0, v160
	v_add_f32_e32 v157, 1.0, v157
	v_add_f32_e32 v161, 1.0, v161
	v_add_f32_e32 v148, 1.0, v148
	v_add_f32_e32 v162, 1.0, v158
	v_add_f32_e32 v149, 1.0, v149
	v_add_f32_e32 v163, 1.0, v159
	v_rcp_f32_e32 v156, v156
	v_rcp_f32_e32 v160, v160
	v_rcp_f32_e32 v157, v157
	v_rcp_f32_e32 v161, v161
	v_rcp_f32_e32 v158, v148
	v_rcp_f32_e32 v148, v162
	v_rcp_f32_e32 v159, v149
	v_rcp_f32_e32 v149, v163

; __device__ __forceinline__ unsigned cvt_pk_bf16(float lo, float hi) { f32x2 v = {lo, hi}; bf16x2_t b = __builtin_convertvector(v, bf16x2_t); return __builtin_bit_cast(unsigned, b); }
; __device__ __forceinline__ float sigmoidf_(float x) { return __builtin_amdgcn_rcpf(1.0f + __builtin_amdgcn_exp2f(-1.4426950408889634f * x)); }
;     __device__ __forceinline__ void operator()(const Acc& acc, const Unit& u, int wr, int wc, int fr, int fq) const {
;     ...
;                 for (int bj = 0; bj < 2; ++bj) { f32x4 v0 = acc[ai][bj][m][0], v1 = acc[ai][bj][m][1];
;                     if (mode == 1) { f32x2 a = gelu_pk((f32x2){v0[0], v0[1]}), b = gelu_pk((f32x2){v0[2], v0[3]}), c = gelu_pk((f32x2){v1[0], v1[1]}), d = gelu_pk((f32x2){v1[2], v1[3]});
;                         v0 = (f32x4){a.x, a.y, b.x, b.y}; v1 = (f32x4){c.x, c.y, d.x, d.y}; }
;                     else if (mode == 2) { v0 = v0 + *(const f32x4*)(gbp + bj * HALF); v1 = v1 + *(const f32x4*)(gbp + bj * HALF + 4);
; #pragma unroll
;                         for (int i = 0; i < 4; ++i) { v0[i] = sigmoidf_(v0[i]); v1[i] = sigmoidf_(v1[i]); } }
;                     u32x4 w; w.x = cvt_pk_bf16(v0[0], v0[1]); w.y = cvt_pk_bf16(v0[2], v0[3]); w.z = cvt_pk_bf16(v1[0], v1[1]); w.w = cvt_pk_bf16(v1[2], v1[3]);
;                     *(u32x4*)(rowp + (mode == 0 ? (size_t)bj * SEQ * 128 : (size_t)bj * HALF)) = w; } }
.LBB0_197:
	v_cvt_pk_bf16_f32 v156, v156, v157
	v_cvt_pk_bf16_f32 v157, v158, v159
	v_cvt_pk_bf16_f32 v159, v148, v149
	v_cndmask_b32_e64 v148, 0, 1, s[24:25]
	v_cvt_pk_bf16_f32 v158, v160, v161
	v_cmp_ne_u32_e64 s[48:49], 1, v148
	s_andn2_b64 vcc, exec, s[24:25]
	s_mov_b64 s[18:19], -1
	global_store_dwordx4 v[146:147], v[156:159], off
	s_cbranch_vccnz .LBB0_201
	s_and_b64 vcc, exec, s[44:45]
	v_mov_b32_e32 v149, v115
	v_mov_b32_e32 v148, v114
	v_mov_b32_e32 v161, v113
	v_mov_b32_e32 v160, v112
	v_mov_b32_e32 v159, v119
	v_mov_b32_e32 v158, v118
	v_mov_b32_e32 v157, v117
	v_mov_b32_e32 v156, v116
	s_cbranch_vccnz .LBB0_200
	v_mov_b32_e32 v156, v240
	v_mov_b32_e32 v157, v241
	v_mov_b32_e32 v158, v242
	v_mov_b32_e32 v159, v243
	v_mov_b32_e32 v160, v244
	v_mov_b32_e32 v161, v245
	v_mov_b32_e32 v162, v246
	v_mov_b32_e32 v163, v247
	v_pk_add_f32 v[148:149], v[118:119], v[158:159]
	v_pk_add_f32 v[156:157], v[116:117], v[156:157]
	v_pk_add_f32 v[158:159], v[114:115], v[162:163]
	v_pk_add_f32 v[160:161], v[112:113], v[160:161]
	v_mul_f32_e32 v156, 0xbfb8aa3b, v156
	v_mul_f32_e32 v160, 0xbfb8aa3b, v160
	v_mul_f32_e32 v157, 0xbfb8aa3b, v157
	v_mul_f32_e32 v161, 0xbfb8aa3b, v161
	v_mul_f32_e32 v148, 0xbfb8aa3b, v148
	v_mul_f32_e32 v158, 0xbfb8aa3b, v158
	v_mul_f32_e32 v149, 0xbfb8aa3b, v149
	v_mul_f32_e32 v159, 0xbfb8aa3b, v159
	v_exp_f32_e32 v156, v156
	v_exp_f32_e32 v160, v160
	v_exp_f32_e32 v157, v157
	v_exp_f32_e32 v161, v161
	v_exp_f32_e32 v148, v148
	v_exp_f32_e32 v158, v158
	v_exp_f32_e32 v149, v149
	v_exp_f32_e32 v159, v159
	v_add_f32_e32 v156, 1.0, v156
	v_add_f32_e32 v160, 1.0, v160
	v_add_f32_e32 v157, 1.0, v157
	v_add_f32_e32 v161, 1.0, v161
	v_add_f32_e32 v148, 1.0, v148
	v_add_f32_e32 v162, 1.0, v158
	v_add_f32_e32 v149, 1.0, v149
	v_add_f32_e32 v163, 1.0, v159
	v_rcp_f32_e32 v156, v156
	v_rcp_f32_e32 v160, v160
	v_rcp_f32_e32 v157, v157
	v_rcp_f32_e32 v161, v161
	v_rcp_f32_e32 v158, v148
	v_rcp_f32_e32 v148, v162
	v_rcp_f32_e32 v159, v149
	v_rcp_f32_e32 v149, v163

; __device__ __forceinline__ unsigned cvt_pk_bf16(float lo, float hi) { f32x2 v = {lo, hi}; bf16x2_t b = __builtin_convertvector(v, bf16x2_t); return __builtin_bit_cast(unsigned, b); }
; __device__ __forceinline__ float sigmoidf_(float x) { return __builtin_amdgcn_rcpf(1.0f + __builtin_amdgcn_exp2f(-1.4426950408889634f * x)); }
;     __device__ __forceinline__ void operator()(const Acc& acc, const Unit& u, int wr, int wc, int fr, int fq) const {
;     ...
;                 for (int bj = 0; bj < 2; ++bj) { f32x4 v0 = acc[ai][bj][m][0], v1 = acc[ai][bj][m][1];
;                     if (mode == 1) { f32x2 a = gelu_pk((f32x2){v0[0], v0[1]}), b = gelu_pk((f32x2){v0[2], v0[3]}), c = gelu_pk((f32x2){v1[0], v1[1]}), d = gelu_pk((f32x2){v1[2], v1[3]});
;                         v0 = (f32x4){a.x, a.y, b.x, b.y}; v1 = (f32x4){c.x, c.y, d.x, d.y}; }
;                     else if (mode == 2) { v0 = v0 + *(const f32x4*)(gbp + bj * HALF); v1 = v1 + *(const f32x4*)(gbp + bj * HALF + 4);
; #pragma unroll
;                         for (int i = 0; i < 4; ++i) { v0[i] = sigmoidf_(v0[i]); v1[i] = sigmoidf_(v1[i]); } }
;                     u32x4 w; w.x = cvt_pk_bf16(v0[0], v0[1]); w.y = cvt_pk_bf16(v0[2], v0[3]); w.z = cvt_pk_bf16(v1[0], v1[1]); w.w = cvt_pk_bf16(v1[2], v1[3]);
;                     *(u32x4*)(rowp + (mode == 0 ? (size_t)bj * SEQ * 128 : (size_t)bj * HALF)) = w; } }
.LBB0_206:
	s_and_b64 vcc, exec, s[44:45]
	v_mov_b32_e32 v149, v107
	v_mov_b32_e32 v148, v106
	v_mov_b32_e32 v161, v105
	v_mov_b32_e32 v160, v104
	v_mov_b32_e32 v159, v111
	v_mov_b32_e32 v158, v110
	v_mov_b32_e32 v157, v109
	v_mov_b32_e32 v156, v108
	s_cbranch_vccnz .LBB0_208
	v_mov_b32_e32 v156, v232
	v_mov_b32_e32 v157, v233
	v_mov_b32_e32 v158, v234
	v_mov_b32_e32 v159, v235
	v_mov_b32_e32 v160, v236
	v_mov_b32_e32 v161, v237
	v_mov_b32_e32 v162, v238
	v_mov_b32_e32 v163, v239
	v_pk_add_f32 v[148:149], v[110:111], v[158:159]
	v_pk_add_f32 v[156:157], v[108:109], v[156:157]
	v_pk_add_f32 v[158:159], v[106:107], v[162:163]
	v_pk_add_f32 v[160:161], v[104:105], v[160:161]
	v_mul_f32_e32 v156, 0xbfb8aa3b, v156
	v_mul_f32_e32 v160, 0xbfb8aa3b, v160
	v_mul_f32_e32 v157, 0xbfb8aa3b, v157
	v_mul_f32_e32 v161, 0xbfb8aa3b, v161
	v_mul_f32_e32 v148, 0xbfb8aa3b, v148
	v_mul_f32_e32 v158, 0xbfb8aa3b, v158
	v_mul_f32_e32 v149, 0xbfb8aa3b, v149
	v_mul_f32_e32 v159, 0xbfb8aa3b, v159
	v_exp_f32_e32 v156, v156
	v_exp_f32_e32 v160, v160
	v_exp_f32_e32 v157, v157
	v_exp_f32_e32 v161, v161
	v_exp_f32_e32 v148, v148
	v_exp_f32_e32 v158, v158
	v_exp_f32_e32 v149, v149
	v_exp_f32_e32 v159, v159
	v_add_f32_e32 v156, 1.0, v156
	v_add_f32_e32 v160, 1.0, v160
	v_add_f32_e32 v157, 1.0, v157
	v_add_f32_e32 v161, 1.0, v161
	v_add_f32_e32 v148, 1.0, v148
	v_add_f32_e32 v162, 1.0, v158
	v_add_f32_e32 v149, 1.0, v149
	v_add_f32_e32 v163, 1.0, v159
	v_rcp_f32_e32 v156, v156
	v_rcp_f32_e32 v160, v160
	v_rcp_f32_e32 v157, v157
	v_rcp_f32_e32 v161, v161
	v_rcp_f32_e32 v158, v148
	v_rcp_f32_e32 v148, v162
	v_rcp_f32_e32 v159, v149
	v_rcp_f32_e32 v149, v163

; __device__ __forceinline__ unsigned cvt_pk_bf16(float lo, float hi) { f32x2 v = {lo, hi}; bf16x2_t b = __builtin_convertvector(v, bf16x2_t); return __builtin_bit_cast(unsigned, b); }
; __device__ __forceinline__ float sigmoidf_(float x) { return __builtin_amdgcn_rcpf(1.0f + __builtin_amdgcn_exp2f(-1.4426950408889634f * x)); }
;     __device__ __forceinline__ void operator()(const Acc& acc, const Unit& u, int wr, int wc, int fr, int fq) const {
;     ...
;                 for (int bj = 0; bj < 2; ++bj) { f32x4 v0 = acc[ai][bj][m][0], v1 = acc[ai][bj][m][1];
;                     if (mode == 1) { f32x2 a = gelu_pk((f32x2){v0[0], v0[1]}), b = gelu_pk((f32x2){v0[2], v0[3]}), c = gelu_pk((f32x2){v1[0], v1[1]}), d = gelu_pk((f32x2){v1[2], v1[3]});
;                         v0 = (f32x4){a.x, a.y, b.x, b.y}; v1 = (f32x4){c.x, c.y, d.x, d.y}; }
;                     else if (mode == 2) { v0 = v0 + *(const f32x4*)(gbp + bj * HALF); v1 = v1 + *(const f32x4*)(gbp + bj * HALF + 4);
; #pragma unroll
;                         for (int i = 0; i < 4; ++i) { v0[i] = sigmoidf_(v0[i]); v1[i] = sigmoidf_(v1[i]); } }
;                     u32x4 w; w.x = cvt_pk_bf16(v0[0], v0[1]); w.y = cvt_pk_bf16(v0[2], v0[3]); w.z = cvt_pk_bf16(v1[0], v1[1]); w.w = cvt_pk_bf16(v1[2], v1[3]);
;                     *(u32x4*)(rowp + (mode == 0 ? (size_t)bj * SEQ * 128 : (size_t)bj * HALF)) = w; } }
.LBB0_211:
	v_cvt_pk_bf16_f32 v156, v156, v157
	v_cvt_pk_bf16_f32 v157, v158, v159
	v_cvt_pk_bf16_f32 v158, v160, v161
	v_cvt_pk_bf16_f32 v159, v148, v149
	s_and_b64 vcc, exec, s[48:49]
	s_mov_b64 s[18:19], -1
	global_store_dwordx4 v[146:147], v[156:159], off
	s_cbranch_vccnz .LBB0_215
	s_and_b64 vcc, exec, s[44:45]
	v_mov_b32_e32 v149, v99
	v_mov_b32_e32 v148, v98
	v_mov_b32_e32 v161, v97
	v_mov_b32_e32 v160, v96
	v_mov_b32_e32 v159, v103
	v_mov_b32_e32 v158, v102
	v_mov_b32_e32 v157, v101
	v_mov_b32_e32 v156, v100
	s_cbranch_vccnz .LBB0_214
	v_mov_b32_e32 v156, v240
	v_mov_b32_e32 v157, v241
	v_mov_b32_e32 v158, v242
	v_mov_b32_e32 v159, v243
	v_mov_b32_e32 v160, v244
	v_mov_b32_e32 v161, v245
	v_mov_b32_e32 v162, v246
	v_mov_b32_e32 v163, v247
	v_pk_add_f32 v[148:149], v[102:103], v[158:159]
	v_pk_add_f32 v[156:157], v[100:101], v[156:157]
	v_pk_add_f32 v[158:159], v[98:99], v[162:163]
	v_pk_add_f32 v[160:161], v[96:97], v[160:161]
	v_mul_f32_e32 v156, 0xbfb8aa3b, v156
	v_mul_f32_e32 v160, 0xbfb8aa3b, v160
	v_mul_f32_e32 v157, 0xbfb8aa3b, v157
	v_mul_f32_e32 v161, 0xbfb8aa3b, v161
	v_mul_f32_e32 v148, 0xbfb8aa3b, v148
	v_mul_f32_e32 v158, 0xbfb8aa3b, v158
	v_mul_f32_e32 v149, 0xbfb8aa3b, v149
	v_mul_f32_e32 v159, 0xbfb8aa3b, v159
	v_exp_f32_e32 v156, v156
	v_exp_f32_e32 v160, v160
	v_exp_f32_e32 v157, v157
	v_exp_f32_e32 v161, v161
	v_exp_f32_e32 v148, v148
	v_exp_f32_e32 v158, v158
	v_exp_f32_e32 v149, v149
	v_exp_f32_e32 v159, v159
	v_add_f32_e32 v156, 1.0, v156
	v_add_f32_e32 v160, 1.0, v160
	v_add_f32_e32 v157, 1.0, v157
	v_add_f32_e32 v161, 1.0, v161
	v_add_f32_e32 v148, 1.0, v148
	v_add_f32_e32 v162, 1.0, v158
	v_add_f32_e32 v149, 1.0, v149
	v_add_f32_e32 v163, 1.0, v159
	v_rcp_f32_e32 v156, v156
	v_rcp_f32_e32 v160, v160
	v_rcp_f32_e32 v157, v157
	v_rcp_f32_e32 v161, v161
	v_rcp_f32_e32 v158, v148
	v_rcp_f32_e32 v148, v162
	v_rcp_f32_e32 v159, v149
	v_rcp_f32_e32 v149, v163

; __device__ __forceinline__ unsigned cvt_pk_bf16(float lo, float hi) { f32x2 v = {lo, hi}; bf16x2_t b = __builtin_convertvector(v, bf16x2_t); return __builtin_bit_cast(unsigned, b); }
; __device__ __forceinline__ float sigmoidf_(float x) { return __builtin_amdgcn_rcpf(1.0f + __builtin_amdgcn_exp2f(-1.4426950408889634f * x)); }
;     __device__ __forceinline__ void operator()(const Acc& acc, const Unit& u, int wr, int wc, int fr, int fq) const {
;     ...
;                 for (int bj = 0; bj < 2; ++bj) { f32x4 v0 = acc[ai][bj][m][0], v1 = acc[ai][bj][m][1];
;                     if (mode == 1) { f32x2 a = gelu_pk((f32x2){v0[0], v0[1]}), b = gelu_pk((f32x2){v0[2], v0[3]}), c = gelu_pk((f32x2){v1[0], v1[1]}), d = gelu_pk((f32x2){v1[2], v1[3]});
;                         v0 = (f32x4){a.x, a.y, b.x, b.y}; v1 = (f32x4){c.x, c.y, d.x, d.y}; }
;                     else if (mode == 2) { v0 = v0 + *(const f32x4*)(gbp + bj * HALF); v1 = v1 + *(const f32x4*)(gbp + bj * HALF + 4);
; #pragma unroll
;                         for (int i = 0; i < 4; ++i) { v0[i] = sigmoidf_(v0[i]); v1[i] = sigmoidf_(v1[i]); } }
;                     u32x4 w; w.x = cvt_pk_bf16(v0[0], v0[1]); w.y = cvt_pk_bf16(v0[2], v0[3]); w.z = cvt_pk_bf16(v1[0], v1[1]); w.w = cvt_pk_bf16(v1[2], v1[3]);
;                     *(u32x4*)(rowp + (mode == 0 ? (size_t)bj * SEQ * 128 : (size_t)bj * HALF)) = w; } }
.LBB0_220:
	s_and_b64 vcc, exec, s[44:45]
	v_mov_b32_e32 v149, v91
	v_mov_b32_e32 v148, v90
	v_mov_b32_e32 v161, v89
	v_mov_b32_e32 v160, v88
	v_mov_b32_e32 v159, v95
	v_mov_b32_e32 v158, v94
	v_mov_b32_e32 v157, v93
	v_mov_b32_e32 v156, v92
	s_cbranch_vccnz .LBB0_222
	v_mov_b32_e32 v156, v232
	v_mov_b32_e32 v157, v233
	v_mov_b32_e32 v158, v234
	v_mov_b32_e32 v159, v235
	v_mov_b32_e32 v160, v236
	v_mov_b32_e32 v161, v237
	v_mov_b32_e32 v162, v238
	v_mov_b32_e32 v163, v239
	v_pk_add_f32 v[148:149], v[94:95], v[158:159]
	v_pk_add_f32 v[156:157], v[92:93], v[156:157]
	v_pk_add_f32 v[158:159], v[90:91], v[162:163]
	v_pk_add_f32 v[160:161], v[88:89], v[160:161]
	v_mul_f32_e32 v156, 0xbfb8aa3b, v156
	v_mul_f32_e32 v160, 0xbfb8aa3b, v160
	v_mul_f32_e32 v157, 0xbfb8aa3b, v157
	v_mul_f32_e32 v161, 0xbfb8aa3b, v161
	v_mul_f32_e32 v148, 0xbfb8aa3b, v148
	v_mul_f32_e32 v158, 0xbfb8aa3b, v158
	v_mul_f32_e32 v149, 0xbfb8aa3b, v149
	v_mul_f32_e32 v159, 0xbfb8aa3b, v159
	v_exp_f32_e32 v156, v156
	v_exp_f32_e32 v160, v160
	v_exp_f32_e32 v157, v157
	v_exp_f32_e32 v161, v161
	v_exp_f32_e32 v148, v148
	v_exp_f32_e32 v158, v158
	v_exp_f32_e32 v149, v149
	v_exp_f32_e32 v159, v159
	v_add_f32_e32 v156, 1.0, v156
	v_add_f32_e32 v160, 1.0, v160
	v_add_f32_e32 v157, 1.0, v157
	v_add_f32_e32 v161, 1.0, v161
	v_add_f32_e32 v148, 1.0, v148
	v_add_f32_e32 v162, 1.0, v158
	v_add_f32_e32 v149, 1.0, v149
	v_add_f32_e32 v163, 1.0, v159
	v_rcp_f32_e32 v156, v156
	v_rcp_f32_e32 v160, v160
	v_rcp_f32_e32 v157, v157
	v_rcp_f32_e32 v161, v161
	v_rcp_f32_e32 v158, v148
	v_rcp_f32_e32 v148, v162
	v_rcp_f32_e32 v159, v149
	v_rcp_f32_e32 v149, v163

; __device__ __forceinline__ unsigned cvt_pk_bf16(float lo, float hi) { f32x2 v = {lo, hi}; bf16x2_t b = __builtin_convertvector(v, bf16x2_t); return __builtin_bit_cast(unsigned, b); }
; __device__ __forceinline__ float sigmoidf_(float x) { return __builtin_amdgcn_rcpf(1.0f + __builtin_amdgcn_exp2f(-1.4426950408889634f * x)); }
;     __device__ __forceinline__ void operator()(const Acc& acc, const Unit& u, int wr, int wc, int fr, int fq) const {
;     ...
;                 for (int bj = 0; bj < 2; ++bj) { f32x4 v0 = acc[ai][bj][m][0], v1 = acc[ai][bj][m][1];
;                     if (mode == 1) { f32x2 a = gelu_pk((f32x2){v0[0], v0[1]}), b = gelu_pk((f32x2){v0[2], v0[3]}), c = gelu_pk((f32x2){v1[0], v1[1]}), d = gelu_pk((f32x2){v1[2], v1[3]});
;                         v0 = (f32x4){a.x, a.y, b.x, b.y}; v1 = (f32x4){c.x, c.y, d.x, d.y}; }
;                     else if (mode == 2) { v0 = v0 + *(const f32x4*)(gbp + bj * HALF); v1 = v1 + *(const f32x4*)(gbp + bj * HALF + 4);
; #pragma unroll
;                         for (int i = 0; i < 4; ++i) { v0[i] = sigmoidf_(v0[i]); v1[i] = sigmoidf_(v1[i]); } }
;                     u32x4 w; w.x = cvt_pk_bf16(v0[0], v0[1]); w.y = cvt_pk_bf16(v0[2], v0[3]); w.z = cvt_pk_bf16(v1[0], v1[1]); w.w = cvt_pk_bf16(v1[2], v1[3]);
;                     *(u32x4*)(rowp + (mode == 0 ? (size_t)bj * SEQ * 128 : (size_t)bj * HALF)) = w; } }
.LBB0_225:
	v_cvt_pk_bf16_f32 v156, v156, v157
	v_cvt_pk_bf16_f32 v157, v158, v159
	v_cvt_pk_bf16_f32 v158, v160, v161
	v_cvt_pk_bf16_f32 v159, v148, v149
	s_and_b64 vcc, exec, s[48:49]
	s_mov_b64 s[18:19], -1
	global_store_dwordx4 v[146:147], v[156:159], off
	s_cbranch_vccnz .LBB0_229
	s_and_b64 vcc, exec, s[44:45]
	v_mov_b32_e32 v149, v83
	v_mov_b32_e32 v148, v82
	v_mov_b32_e32 v161, v81
	v_mov_b32_e32 v160, v80
	v_mov_b32_e32 v159, v87
	v_mov_b32_e32 v158, v86
	v_mov_b32_e32 v157, v85
	v_mov_b32_e32 v156, v84
	s_cbranch_vccnz .LBB0_228
	v_mov_b32_e32 v156, v240
	v_mov_b32_e32 v157, v241
	v_mov_b32_e32 v158, v242
	v_mov_b32_e32 v159, v243
	v_mov_b32_e32 v160, v244
	v_mov_b32_e32 v161, v245
	v_mov_b32_e32 v162, v246
	v_mov_b32_e32 v163, v247
	v_pk_add_f32 v[148:149], v[86:87], v[158:159]
	v_pk_add_f32 v[156:157], v[84:85], v[156:157]
	v_pk_add_f32 v[158:159], v[82:83], v[162:163]
	v_pk_add_f32 v[160:161], v[80:81], v[160:161]
	v_mul_f32_e32 v156, 0xbfb8aa3b, v156
	v_mul_f32_e32 v160, 0xbfb8aa3b, v160
	v_mul_f32_e32 v157, 0xbfb8aa3b, v157
	v_mul_f32_e32 v161, 0xbfb8aa3b, v161
	v_mul_f32_e32 v148, 0xbfb8aa3b, v148
	v_mul_f32_e32 v158, 0xbfb8aa3b, v158
	v_mul_f32_e32 v149, 0xbfb8aa3b, v149
	v_mul_f32_e32 v159, 0xbfb8aa3b, v159
	v_exp_f32_e32 v156, v156
	v_exp_f32_e32 v160, v160
	v_exp_f32_e32 v157, v157
	v_exp_f32_e32 v161, v161
	v_exp_f32_e32 v148, v148
	v_exp_f32_e32 v158, v158
	v_exp_f32_e32 v149, v149
	v_exp_f32_e32 v159, v159
	v_add_f32_e32 v156, 1.0, v156
	v_add_f32_e32 v160, 1.0, v160
	v_add_f32_e32 v157, 1.0, v157
	v_add_f32_e32 v161, 1.0, v161
	v_add_f32_e32 v148, 1.0, v148
	v_add_f32_e32 v162, 1.0, v158
	v_add_f32_e32 v149, 1.0, v149
	v_add_f32_e32 v163, 1.0, v159
	v_rcp_f32_e32 v156, v156
	v_rcp_f32_e32 v160, v160
	v_rcp_f32_e32 v157, v157
	v_rcp_f32_e32 v161, v161
	v_rcp_f32_e32 v158, v148
	v_rcp_f32_e32 v148, v162
	v_rcp_f32_e32 v159, v149
	v_rcp_f32_e32 v149, v163

; __device__ __forceinline__ unsigned cvt_pk_bf16(float lo, float hi) { f32x2 v = {lo, hi}; bf16x2_t b = __builtin_convertvector(v, bf16x2_t); return __builtin_bit_cast(unsigned, b); }
; __device__ __forceinline__ float sigmoidf_(float x) { return __builtin_amdgcn_rcpf(1.0f + __builtin_amdgcn_exp2f(-1.4426950408889634f * x)); }
;     __device__ __forceinline__ void operator()(const Acc& acc, const Unit& u, int wr, int wc, int fr, int fq) const {
;     ...
;                 for (int bj = 0; bj < 2; ++bj) { f32x4 v0 = acc[ai][bj][m][0], v1 = acc[ai][bj][m][1];
;                     if (mode == 1) { f32x2 a = gelu_pk((f32x2){v0[0], v0[1]}), b = gelu_pk((f32x2){v0[2], v0[3]}), c = gelu_pk((f32x2){v1[0], v1[1]}), d = gelu_pk((f32x2){v1[2], v1[3]});
;                         v0 = (f32x4){a.x, a.y, b.x, b.y}; v1 = (f32x4){c.x, c.y, d.x, d.y}; }
;                     else if (mode == 2) { v0 = v0 + *(const f32x4*)(gbp + bj * HALF); v1 = v1 + *(const f32x4*)(gbp + bj * HALF + 4);
; #pragma unroll
;                         for (int i = 0; i < 4; ++i) { v0[i] = sigmoidf_(v0[i]); v1[i] = sigmoidf_(v1[i]); } }
;                     u32x4 w; w.x = cvt_pk_bf16(v0[0], v0[1]); w.y = cvt_pk_bf16(v0[2], v0[3]); w.z = cvt_pk_bf16(v1[0], v1[1]); w.w = cvt_pk_bf16(v1[2], v1[3]);
;                     *(u32x4*)(rowp + (mode == 0 ? (size_t)bj * SEQ * 128 : (size_t)bj * HALF)) = w; } }
.LBB0_234:
	s_and_b64 vcc, exec, s[44:45]
	v_mov_b32_e32 v149, v75
	v_mov_b32_e32 v148, v74
	v_mov_b32_e32 v161, v73
	v_mov_b32_e32 v160, v72
	v_mov_b32_e32 v159, v79
	v_mov_b32_e32 v158, v78
	v_mov_b32_e32 v157, v77
	v_mov_b32_e32 v156, v76
	s_cbranch_vccnz .LBB0_236
	v_mov_b32_e32 v156, v232
	v_mov_b32_e32 v157, v233
	v_mov_b32_e32 v158, v234
	v_mov_b32_e32 v159, v235
	v_mov_b32_e32 v160, v236
	v_mov_b32_e32 v161, v237
	v_mov_b32_e32 v162, v238
	v_mov_b32_e32 v163, v239
	v_pk_add_f32 v[148:149], v[78:79], v[158:159]
	v_pk_add_f32 v[156:157], v[76:77], v[156:157]
	v_pk_add_f32 v[158:159], v[74:75], v[162:163]
	v_pk_add_f32 v[160:161], v[72:73], v[160:161]
	v_mul_f32_e32 v156, 0xbfb8aa3b, v156
	v_mul_f32_e32 v160, 0xbfb8aa3b, v160
	v_mul_f32_e32 v157, 0xbfb8aa3b, v157
	v_mul_f32_e32 v161, 0xbfb8aa3b, v161
	v_mul_f32_e32 v148, 0xbfb8aa3b, v148
	v_mul_f32_e32 v158, 0xbfb8aa3b, v158
	v_mul_f32_e32 v149, 0xbfb8aa3b, v149
	v_mul_f32_e32 v159, 0xbfb8aa3b, v159
	v_exp_f32_e32 v156, v156
	v_exp_f32_e32 v160, v160
	v_exp_f32_e32 v157, v157
	v_exp_f32_e32 v161, v161
	v_exp_f32_e32 v148, v148
	v_exp_f32_e32 v158, v158
	v_exp_f32_e32 v149, v149
	v_exp_f32_e32 v159, v159
	v_add_f32_e32 v156, 1.0, v156
	v_add_f32_e32 v160, 1.0, v160
	v_add_f32_e32 v157, 1.0, v157
	v_add_f32_e32 v161, 1.0, v161
	v_add_f32_e32 v148, 1.0, v148
	v_add_f32_e32 v162, 1.0, v158
	v_add_f32_e32 v149, 1.0, v149
	v_add_f32_e32 v163, 1.0, v159
	v_rcp_f32_e32 v156, v156
	v_rcp_f32_e32 v160, v160
	v_rcp_f32_e32 v157, v157
	v_rcp_f32_e32 v161, v161
	v_rcp_f32_e32 v158, v148
	v_rcp_f32_e32 v148, v162
	v_rcp_f32_e32 v159, v149
	v_rcp_f32_e32 v149, v163

; __device__ __forceinline__ unsigned cvt_pk_bf16(float lo, float hi) { f32x2 v = {lo, hi}; bf16x2_t b = __builtin_convertvector(v, bf16x2_t); return __builtin_bit_cast(unsigned, b); }
; __device__ __forceinline__ float sigmoidf_(float x) { return __builtin_amdgcn_rcpf(1.0f + __builtin_amdgcn_exp2f(-1.4426950408889634f * x)); }
;     __device__ __forceinline__ void operator()(const Acc& acc, const Unit& u, int wr, int wc, int fr, int fq) const {
;     ...
;                 for (int bj = 0; bj < 2; ++bj) { f32x4 v0 = acc[ai][bj][m][0], v1 = acc[ai][bj][m][1];
;                     if (mode == 1) { f32x2 a = gelu_pk((f32x2){v0[0], v0[1]}), b = gelu_pk((f32x2){v0[2], v0[3]}), c = gelu_pk((f32x2){v1[0], v1[1]}), d = gelu_pk((f32x2){v1[2], v1[3]});
;                         v0 = (f32x4){a.x, a.y, b.x, b.y}; v1 = (f32x4){c.x, c.y, d.x, d.y}; }
;                     else if (mode == 2) { v0 = v0 + *(const f32x4*)(gbp + bj * HALF); v1 = v1 + *(const f32x4*)(gbp + bj * HALF + 4);
; #pragma unroll
;                         for (int i = 0; i < 4; ++i) { v0[i] = sigmoidf_(v0[i]); v1[i] = sigmoidf_(v1[i]); } }
;                     u32x4 w; w.x = cvt_pk_bf16(v0[0], v0[1]); w.y = cvt_pk_bf16(v0[2], v0[3]); w.z = cvt_pk_bf16(v1[0], v1[1]); w.w = cvt_pk_bf16(v1[2], v1[3]);
;                     *(u32x4*)(rowp + (mode == 0 ? (size_t)bj * SEQ * 128 : (size_t)bj * HALF)) = w; } }
.LBB0_239:
	v_cvt_pk_bf16_f32 v156, v156, v157
	v_cvt_pk_bf16_f32 v157, v158, v159
	v_cvt_pk_bf16_f32 v158, v160, v161
	v_cvt_pk_bf16_f32 v159, v148, v149
	s_and_b64 vcc, exec, s[48:49]
	s_mov_b64 s[18:19], -1
	global_store_dwordx4 v[146:147], v[156:159], off
	s_cbranch_vccnz .LBB0_243
	s_and_b64 vcc, exec, s[44:45]
	v_mov_b32_e32 v149, v67
	v_mov_b32_e32 v148, v66
	v_mov_b32_e32 v161, v65
	v_mov_b32_e32 v160, v64
	v_mov_b32_e32 v159, v71
	v_mov_b32_e32 v158, v70
	v_mov_b32_e32 v157, v69
	v_mov_b32_e32 v156, v68
	s_cbranch_vccnz .LBB0_242
	v_mov_b32_e32 v156, v240
	v_mov_b32_e32 v157, v241
	v_mov_b32_e32 v158, v242
	v_mov_b32_e32 v159, v243
	v_mov_b32_e32 v160, v244
	v_mov_b32_e32 v161, v245
	v_mov_b32_e32 v162, v246
	v_mov_b32_e32 v163, v247
	v_pk_add_f32 v[148:149], v[70:71], v[158:159]
	v_pk_add_f32 v[156:157], v[68:69], v[156:157]
	v_pk_add_f32 v[158:159], v[66:67], v[162:163]
	v_pk_add_f32 v[160:161], v[64:65], v[160:161]
	v_mul_f32_e32 v156, 0xbfb8aa3b, v156
	v_mul_f32_e32 v160, 0xbfb8aa3b, v160
	v_mul_f32_e32 v157, 0xbfb8aa3b, v157
	v_mul_f32_e32 v161, 0xbfb8aa3b, v161
	v_mul_f32_e32 v148, 0xbfb8aa3b, v148
	v_mul_f32_e32 v158, 0xbfb8aa3b, v158
	v_mul_f32_e32 v149, 0xbfb8aa3b, v149
	v_mul_f32_e32 v159, 0xbfb8aa3b, v159
	v_exp_f32_e32 v156, v156
	v_exp_f32_e32 v160, v160
	v_exp_f32_e32 v157, v157
	v_exp_f32_e32 v161, v161
	v_exp_f32_e32 v148, v148
	v_exp_f32_e32 v158, v158
	v_exp_f32_e32 v149, v149
	v_exp_f32_e32 v159, v159
	v_add_f32_e32 v156, 1.0, v156
	v_add_f32_e32 v160, 1.0, v160
	v_add_f32_e32 v157, 1.0, v157
	v_add_f32_e32 v161, 1.0, v161
	v_add_f32_e32 v148, 1.0, v148
	v_add_f32_e32 v162, 1.0, v158
	v_add_f32_e32 v149, 1.0, v149
	v_add_f32_e32 v163, 1.0, v159
	v_rcp_f32_e32 v156, v156
	v_rcp_f32_e32 v160, v160
	v_rcp_f32_e32 v157, v157
	v_rcp_f32_e32 v161, v161
	v_rcp_f32_e32 v158, v148
	v_rcp_f32_e32 v148, v162
	v_rcp_f32_e32 v159, v149
	v_rcp_f32_e32 v149, v163

; __device__ __forceinline__ unsigned cvt_pk_bf16(float lo, float hi) { f32x2 v = {lo, hi}; bf16x2_t b = __builtin_convertvector(v, bf16x2_t); return __builtin_bit_cast(unsigned, b); }
; __device__ __forceinline__ float sigmoidf_(float x) { return __builtin_amdgcn_rcpf(1.0f + __builtin_amdgcn_exp2f(-1.4426950408889634f * x)); }
;     __device__ __forceinline__ void operator()(const Acc& acc, const Unit& u, int wr, int wc, int fr, int fq) const {
;     ...
;                 for (int bj = 0; bj < 2; ++bj) { f32x4 v0 = acc[ai][bj][m][0], v1 = acc[ai][bj][m][1];
;                     if (mode == 1) { f32x2 a = gelu_pk((f32x2){v0[0], v0[1]}), b = gelu_pk((f32x2){v0[2], v0[3]}), c = gelu_pk((f32x2){v1[0], v1[1]}), d = gelu_pk((f32x2){v1[2], v1[3]});
;                         v0 = (f32x4){a.x, a.y, b.x, b.y}; v1 = (f32x4){c.x, c.y, d.x, d.y}; }
;                     else if (mode == 2) { v0 = v0 + *(const f32x4*)(gbp + bj * HALF); v1 = v1 + *(const f32x4*)(gbp + bj * HALF + 4);
; #pragma unroll
;                         for (int i = 0; i < 4; ++i) { v0[i] = sigmoidf_(v0[i]); v1[i] = sigmoidf_(v1[i]); } }
;                     u32x4 w; w.x = cvt_pk_bf16(v0[0], v0[1]); w.y = cvt_pk_bf16(v0[2], v0[3]); w.z = cvt_pk_bf16(v1[0], v1[1]); w.w = cvt_pk_bf16(v1[2], v1[3]);
;                     *(u32x4*)(rowp + (mode == 0 ? (size_t)bj * SEQ * 128 : (size_t)bj * HALF)) = w; } }
.LBB0_248:
	s_and_b64 vcc, exec, s[44:45]
	v_mov_b32_e32 v149, v59
	v_mov_b32_e32 v148, v58
	v_mov_b32_e32 v161, v57
	v_mov_b32_e32 v160, v56
	v_mov_b32_e32 v159, v63
	v_mov_b32_e32 v158, v62
	v_mov_b32_e32 v157, v61
	v_mov_b32_e32 v156, v60
	s_cbranch_vccnz .LBB0_250
	v_mov_b32_e32 v156, v232
	v_mov_b32_e32 v157, v233
	v_mov_b32_e32 v158, v234
	v_mov_b32_e32 v159, v235
	v_mov_b32_e32 v160, v236
	v_mov_b32_e32 v161, v237
	v_mov_b32_e32 v162, v238
	v_mov_b32_e32 v163, v239
	v_pk_add_f32 v[148:149], v[62:63], v[158:159]
	v_pk_add_f32 v[156:157], v[60:61], v[156:157]
	v_pk_add_f32 v[158:159], v[58:59], v[162:163]
	v_pk_add_f32 v[160:161], v[56:57], v[160:161]
	v_mul_f32_e32 v156, 0xbfb8aa3b, v156
	v_mul_f32_e32 v160, 0xbfb8aa3b, v160
	v_mul_f32_e32 v157, 0xbfb8aa3b, v157
	v_mul_f32_e32 v161, 0xbfb8aa3b, v161
	v_mul_f32_e32 v148, 0xbfb8aa3b, v148
	v_mul_f32_e32 v158, 0xbfb8aa3b, v158
	v_mul_f32_e32 v149, 0xbfb8aa3b, v149
	v_mul_f32_e32 v159, 0xbfb8aa3b, v159
	v_exp_f32_e32 v156, v156
	v_exp_f32_e32 v160, v160
	v_exp_f32_e32 v157, v157
	v_exp_f32_e32 v161, v161
	v_exp_f32_e32 v148, v148
	v_exp_f32_e32 v158, v158
	v_exp_f32_e32 v149, v149
	v_exp_f32_e32 v159, v159
	v_add_f32_e32 v156, 1.0, v156
	v_add_f32_e32 v160, 1.0, v160
	v_add_f32_e32 v157, 1.0, v157
	v_add_f32_e32 v161, 1.0, v161
	v_add_f32_e32 v148, 1.0, v148
	v_add_f32_e32 v162, 1.0, v158
	v_add_f32_e32 v149, 1.0, v149
	v_add_f32_e32 v163, 1.0, v159
	v_rcp_f32_e32 v156, v156
	v_rcp_f32_e32 v160, v160
	v_rcp_f32_e32 v157, v157
	v_rcp_f32_e32 v161, v161
	v_rcp_f32_e32 v158, v148
	v_rcp_f32_e32 v148, v162
	v_rcp_f32_e32 v159, v149
	v_rcp_f32_e32 v149, v163

; __device__ __forceinline__ unsigned cvt_pk_bf16(float lo, float hi) { f32x2 v = {lo, hi}; bf16x2_t b = __builtin_convertvector(v, bf16x2_t); return __builtin_bit_cast(unsigned, b); }
; __device__ __forceinline__ float sigmoidf_(float x) { return __builtin_amdgcn_rcpf(1.0f + __builtin_amdgcn_exp2f(-1.4426950408889634f * x)); }
;     __device__ __forceinline__ void operator()(const Acc& acc, const Unit& u, int wr, int wc, int fr, int fq) const {
;     ...
;                 for (int bj = 0; bj < 2; ++bj) { f32x4 v0 = acc[ai][bj][m][0], v1 = acc[ai][bj][m][1];
;                     if (mode == 1) { f32x2 a = gelu_pk((f32x2){v0[0], v0[1]}), b = gelu_pk((f32x2){v0[2], v0[3]}), c = gelu_pk((f32x2){v1[0], v1[1]}), d = gelu_pk((f32x2){v1[2], v1[3]});
;                         v0 = (f32x4){a.x, a.y, b.x, b.y}; v1 = (f32x4){c.x, c.y, d.x, d.y}; }
;                     else if (mode == 2) { v0 = v0 + *(const f32x4*)(gbp + bj * HALF); v1 = v1 + *(const f32x4*)(gbp + bj * HALF + 4);
; #pragma unroll
;                         for (int i = 0; i < 4; ++i) { v0[i] = sigmoidf_(v0[i]); v1[i] = sigmoidf_(v1[i]); } }
;                     u32x4 w; w.x = cvt_pk_bf16(v0[0], v0[1]); w.y = cvt_pk_bf16(v0[2], v0[3]); w.z = cvt_pk_bf16(v1[0], v1[1]); w.w = cvt_pk_bf16(v1[2], v1[3]);
;                     *(u32x4*)(rowp + (mode == 0 ? (size_t)bj * SEQ * 128 : (size_t)bj * HALF)) = w; } }
.LBB0_253:
	v_cvt_pk_bf16_f32 v156, v156, v157
	v_cvt_pk_bf16_f32 v157, v158, v159
	v_cvt_pk_bf16_f32 v158, v160, v161
	v_cvt_pk_bf16_f32 v159, v148, v149
	s_and_b64 vcc, exec, s[48:49]
	s_mov_b64 s[18:19], -1
	global_store_dwordx4 v[146:147], v[156:159], off
	s_cbranch_vccnz .LBB0_257
	s_and_b64 vcc, exec, s[44:45]
	v_mov_b32_e32 v149, v51
	v_mov_b32_e32 v148, v50
	v_mov_b32_e32 v161, v49
	v_mov_b32_e32 v160, v48
	v_mov_b32_e32 v159, v55
	v_mov_b32_e32 v158, v54
	v_mov_b32_e32 v157, v53
	v_mov_b32_e32 v156, v52
	s_cbranch_vccnz .LBB0_256
	v_mov_b32_e32 v156, v240
	v_mov_b32_e32 v157, v241
	v_mov_b32_e32 v158, v242
	v_mov_b32_e32 v159, v243
	v_mov_b32_e32 v160, v244
	v_mov_b32_e32 v161, v245
	v_mov_b32_e32 v162, v246
	v_mov_b32_e32 v163, v247
	v_pk_add_f32 v[148:149], v[54:55], v[158:159]
	v_pk_add_f32 v[156:157], v[52:53], v[156:157]
	v_pk_add_f32 v[158:159], v[50:51], v[162:163]
	v_pk_add_f32 v[160:161], v[48:49], v[160:161]
	v_mul_f32_e32 v156, 0xbfb8aa3b, v156
	v_mul_f32_e32 v160, 0xbfb8aa3b, v160
	v_mul_f32_e32 v157, 0xbfb8aa3b, v157
	v_mul_f32_e32 v161, 0xbfb8aa3b, v161
	v_mul_f32_e32 v148, 0xbfb8aa3b, v148
	v_mul_f32_e32 v158, 0xbfb8aa3b, v158
	v_mul_f32_e32 v149, 0xbfb8aa3b, v149
	v_mul_f32_e32 v159, 0xbfb8aa3b, v159
	v_exp_f32_e32 v156, v156
	v_exp_f32_e32 v160, v160
	v_exp_f32_e32 v157, v157
	v_exp_f32_e32 v161, v161
	v_exp_f32_e32 v148, v148
	v_exp_f32_e32 v158, v158
	v_exp_f32_e32 v149, v149
	v_exp_f32_e32 v159, v159
	v_add_f32_e32 v156, 1.0, v156
	v_add_f32_e32 v160, 1.0, v160
	v_add_f32_e32 v157, 1.0, v157
	v_add_f32_e32 v161, 1.0, v161
	v_add_f32_e32 v148, 1.0, v148
	v_add_f32_e32 v162, 1.0, v158
	v_add_f32_e32 v149, 1.0, v149
	v_add_f32_e32 v163, 1.0, v159
	v_rcp_f32_e32 v156, v156
	v_rcp_f32_e32 v160, v160
	v_rcp_f32_e32 v157, v157
	v_rcp_f32_e32 v161, v161
	v_rcp_f32_e32 v158, v148
	v_rcp_f32_e32 v148, v162
	v_rcp_f32_e32 v159, v149
	v_rcp_f32_e32 v149, v163

; __device__ __forceinline__ unsigned cvt_pk_bf16(float lo, float hi) { f32x2 v = {lo, hi}; bf16x2_t b = __builtin_convertvector(v, bf16x2_t); return __builtin_bit_cast(unsigned, b); }
; __device__ __forceinline__ float sigmoidf_(float x) { return __builtin_amdgcn_rcpf(1.0f + __builtin_amdgcn_exp2f(-1.4426950408889634f * x)); }
;     __device__ __forceinline__ void operator()(const Acc& acc, const Unit& u, int wr, int wc, int fr, int fq) const {
;     ...
;                 for (int bj = 0; bj < 2; ++bj) { f32x4 v0 = acc[ai][bj][m][0], v1 = acc[ai][bj][m][1];
;                     if (mode == 1) { f32x2 a = gelu_pk((f32x2){v0[0], v0[1]}), b = gelu_pk((f32x2){v0[2], v0[3]}), c = gelu_pk((f32x2){v1[0], v1[1]}), d = gelu_pk((f32x2){v1[2], v1[3]});
;                         v0 = (f32x4){a.x, a.y, b.x, b.y}; v1 = (f32x4){c.x, c.y, d.x, d.y}; }
;                     else if (mode == 2) { v0 = v0 + *(const f32x4*)(gbp + bj * HALF); v1 = v1 + *(const f32x4*)(gbp + bj * HALF + 4);
; #pragma unroll
;                         for (int i = 0; i < 4; ++i) { v0[i] = sigmoidf_(v0[i]); v1[i] = sigmoidf_(v1[i]); } }
;                     u32x4 w; w.x = cvt_pk_bf16(v0[0], v0[1]); w.y = cvt_pk_bf16(v0[2], v0[3]); w.z = cvt_pk_bf16(v1[0], v1[1]); w.w = cvt_pk_bf16(v1[2], v1[3]);
;                     *(u32x4*)(rowp + (mode == 0 ? (size_t)bj * SEQ * 128 : (size_t)bj * HALF)) = w; } }
.LBB0_262:
	s_and_b64 vcc, exec, s[44:45]
	v_mov_b32_e32 v149, v43
	v_mov_b32_e32 v148, v42
	v_mov_b32_e32 v161, v41
	v_mov_b32_e32 v160, v40
	v_mov_b32_e32 v159, v47
	v_mov_b32_e32 v158, v46
	v_mov_b32_e32 v157, v45
	v_mov_b32_e32 v156, v44
	s_cbranch_vccnz .LBB0_264
	v_mov_b32_e32 v156, v232
	v_mov_b32_e32 v157, v233
	v_mov_b32_e32 v158, v234
	v_mov_b32_e32 v159, v235
	v_mov_b32_e32 v160, v236
	v_mov_b32_e32 v161, v237
	v_mov_b32_e32 v162, v238
	v_mov_b32_e32 v163, v239
	v_pk_add_f32 v[148:149], v[46:47], v[158:159]
	v_pk_add_f32 v[156:157], v[44:45], v[156:157]
	v_pk_add_f32 v[158:159], v[42:43], v[162:163]
	v_pk_add_f32 v[160:161], v[40:41], v[160:161]
	v_mul_f32_e32 v156, 0xbfb8aa3b, v156
	v_mul_f32_e32 v160, 0xbfb8aa3b, v160
	v_mul_f32_e32 v157, 0xbfb8aa3b, v157
	v_mul_f32_e32 v161, 0xbfb8aa3b, v161
	v_mul_f32_e32 v148, 0xbfb8aa3b, v148
	v_mul_f32_e32 v158, 0xbfb8aa3b, v158
	v_mul_f32_e32 v149, 0xbfb8aa3b, v149
	v_mul_f32_e32 v159, 0xbfb8aa3b, v159
	v_exp_f32_e32 v156, v156
	v_exp_f32_e32 v160, v160
	v_exp_f32_e32 v157, v157
	v_exp_f32_e32 v161, v161
	v_exp_f32_e32 v148, v148
	v_exp_f32_e32 v158, v158
	v_exp_f32_e32 v149, v149
	v_exp_f32_e32 v159, v159
	v_add_f32_e32 v156, 1.0, v156
	v_add_f32_e32 v160, 1.0, v160
	v_add_f32_e32 v157, 1.0, v157
	v_add_f32_e32 v161, 1.0, v161
	v_add_f32_e32 v148, 1.0, v148
	v_add_f32_e32 v162, 1.0, v158
	v_add_f32_e32 v149, 1.0, v149
	v_add_f32_e32 v163, 1.0, v159
	v_rcp_f32_e32 v156, v156
	v_rcp_f32_e32 v160, v160
	v_rcp_f32_e32 v157, v157
	v_rcp_f32_e32 v161, v161
	v_rcp_f32_e32 v158, v148
	v_rcp_f32_e32 v148, v162
	v_rcp_f32_e32 v159, v149
	v_rcp_f32_e32 v149, v163

; __device__ __forceinline__ unsigned cvt_pk_bf16(float lo, float hi) { f32x2 v = {lo, hi}; bf16x2_t b = __builtin_convertvector(v, bf16x2_t); return __builtin_bit_cast(unsigned, b); }
; __device__ __forceinline__ float sigmoidf_(float x) { return __builtin_amdgcn_rcpf(1.0f + __builtin_amdgcn_exp2f(-1.4426950408889634f * x)); }
;     __device__ __forceinline__ void operator()(const Acc& acc, const Unit& u, int wr, int wc, int fr, int fq) const {
;     ...
;                 for (int bj = 0; bj < 2; ++bj) { f32x4 v0 = acc[ai][bj][m][0], v1 = acc[ai][bj][m][1];
;                     if (mode == 1) { f32x2 a = gelu_pk((f32x2){v0[0], v0[1]}), b = gelu_pk((f32x2){v0[2], v0[3]}), c = gelu_pk((f32x2){v1[0], v1[1]}), d = gelu_pk((f32x2){v1[2], v1[3]});
;                         v0 = (f32x4){a.x, a.y, b.x, b.y}; v1 = (f32x4){c.x, c.y, d.x, d.y}; }
;                     else if (mode == 2) { v0 = v0 + *(const f32x4*)(gbp + bj * HALF); v1 = v1 + *(const f32x4*)(gbp + bj * HALF + 4);
; #pragma unroll
;                         for (int i = 0; i < 4; ++i) { v0[i] = sigmoidf_(v0[i]); v1[i] = sigmoidf_(v1[i]); } }
;                     u32x4 w; w.x = cvt_pk_bf16(v0[0], v0[1]); w.y = cvt_pk_bf16(v0[2], v0[3]); w.z = cvt_pk_bf16(v1[0], v1[1]); w.w = cvt_pk_bf16(v1[2], v1[3]);
;                     *(u32x4*)(rowp + (mode == 0 ? (size_t)bj * SEQ * 128 : (size_t)bj * HALF)) = w; } }
.LBB0_267:
	v_cvt_pk_bf16_f32 v156, v156, v157
	v_cvt_pk_bf16_f32 v157, v158, v159
	v_cvt_pk_bf16_f32 v158, v160, v161
	v_cvt_pk_bf16_f32 v159, v148, v149
	s_and_b64 vcc, exec, s[48:49]
	s_mov_b64 s[18:19], -1
	global_store_dwordx4 v[146:147], v[156:159], off
	s_cbranch_vccnz .LBB0_271
	s_and_b64 vcc, exec, s[44:45]
	v_mov_b32_e32 v149, v35
	v_mov_b32_e32 v148, v34
	v_mov_b32_e32 v161, v33
	v_mov_b32_e32 v160, v32
	v_mov_b32_e32 v159, v39
	v_mov_b32_e32 v158, v38
	v_mov_b32_e32 v157, v37
	v_mov_b32_e32 v156, v36
	s_cbranch_vccnz .LBB0_270
	v_mov_b32_e32 v156, v240
	v_mov_b32_e32 v157, v241
	v_mov_b32_e32 v158, v242
	v_mov_b32_e32 v159, v243
	v_mov_b32_e32 v160, v244
	v_mov_b32_e32 v161, v245
	v_mov_b32_e32 v162, v246
	v_mov_b32_e32 v163, v247
	v_pk_add_f32 v[148:149], v[38:39], v[158:159]
	v_pk_add_f32 v[156:157], v[36:37], v[156:157]
	v_pk_add_f32 v[158:159], v[34:35], v[162:163]
	v_pk_add_f32 v[160:161], v[32:33], v[160:161]
	v_mul_f32_e32 v156, 0xbfb8aa3b, v156
	v_mul_f32_e32 v160, 0xbfb8aa3b, v160
	v_mul_f32_e32 v157, 0xbfb8aa3b, v157
	v_mul_f32_e32 v161, 0xbfb8aa3b, v161
	v_mul_f32_e32 v148, 0xbfb8aa3b, v148
	v_mul_f32_e32 v158, 0xbfb8aa3b, v158
	v_mul_f32_e32 v149, 0xbfb8aa3b, v149
	v_mul_f32_e32 v159, 0xbfb8aa3b, v159
	v_exp_f32_e32 v156, v156
	v_exp_f32_e32 v160, v160
	v_exp_f32_e32 v157, v157
	v_exp_f32_e32 v161, v161
	v_exp_f32_e32 v148, v148
	v_exp_f32_e32 v158, v158
	v_exp_f32_e32 v149, v149
	v_exp_f32_e32 v159, v159
	v_add_f32_e32 v156, 1.0, v156
	v_add_f32_e32 v160, 1.0, v160
	v_add_f32_e32 v157, 1.0, v157
	v_add_f32_e32 v161, 1.0, v161
	v_add_f32_e32 v148, 1.0, v148
	v_add_f32_e32 v162, 1.0, v158
	v_add_f32_e32 v149, 1.0, v149
	v_add_f32_e32 v163, 1.0, v159
	v_rcp_f32_e32 v156, v156
	v_rcp_f32_e32 v160, v160
	v_rcp_f32_e32 v157, v157
	v_rcp_f32_e32 v161, v161
	v_rcp_f32_e32 v158, v148
	v_rcp_f32_e32 v148, v162
	v_rcp_f32_e32 v159, v149
	v_rcp_f32_e32 v149, v163

; __device__ __forceinline__ float sigmoidf_(float x) { return __builtin_amdgcn_rcpf(1.0f + __builtin_amdgcn_exp2f(-1.4426950408889634f * x)); }
;     __device__ __forceinline__ void operator()(const Acc& acc, const Unit& u, int wr, int wc, int fr, int fq) const {
;     ...
;                 for (int bj = 0; bj < 2; ++bj) { f32x4 v0 = acc[ai][bj][m][0], v1 = acc[ai][bj][m][1];
;                     if (mode == 1) { f32x2 a = gelu_pk((f32x2){v0[0], v0[1]}), b = gelu_pk((f32x2){v0[2], v0[3]}), c = gelu_pk((f32x2){v1[0], v1[1]}), d = gelu_pk((f32x2){v1[2], v1[3]});
;                         v0 = (f32x4){a.x, a.y, b.x, b.y}; v1 = (f32x4){c.x, c.y, d.x, d.y}; }
;                     else if (mode == 2) { v0 = v0 + *(const f32x4*)(gbp + bj * HALF); v1 = v1 + *(const f32x4*)(gbp + bj * HALF + 4);
; #pragma unroll
;                         for (int i = 0; i < 4; ++i) { v0[i] = sigmoidf_(v0[i]); v1[i] = sigmoidf_(v1[i]); } }
.LBB0_276:
	s_and_b64 vcc, exec, s[44:45]
	v_mov_b32_e32 v149, v27
	v_mov_b32_e32 v148, v26
	v_mov_b32_e32 v161, v25
	v_mov_b32_e32 v160, v24
	v_mov_b32_e32 v159, v31
	v_mov_b32_e32 v158, v30
	v_mov_b32_e32 v157, v29
	v_mov_b32_e32 v156, v28
	s_cbranch_vccnz .LBB0_278
	v_mov_b32_e32 v156, v232
	v_mov_b32_e32 v157, v233
	v_mov_b32_e32 v158, v234
	v_mov_b32_e32 v159, v235
	v_mov_b32_e32 v160, v236
	v_mov_b32_e32 v161, v237
	v_mov_b32_e32 v162, v238
	v_mov_b32_e32 v163, v239
	v_pk_add_f32 v[148:149], v[30:31], v[158:159]
	v_pk_add_f32 v[156:157], v[28:29], v[156:157]
	v_pk_add_f32 v[158:159], v[26:27], v[162:163]
	v_pk_add_f32 v[160:161], v[24:25], v[160:161]
	v_mul_f32_e32 v156, 0xbfb8aa3b, v156
	v_mul_f32_e32 v160, 0xbfb8aa3b, v160
	v_mul_f32_e32 v157, 0xbfb8aa3b, v157
	v_mul_f32_e32 v161, 0xbfb8aa3b, v161
	v_mul_f32_e32 v148, 0xbfb8aa3b, v148
	v_mul_f32_e32 v158, 0xbfb8aa3b, v158
	v_mul_f32_e32 v149, 0xbfb8aa3b, v149
	v_mul_f32_e32 v159, 0xbfb8aa3b, v159
	v_exp_f32_e32 v156, v156
	v_exp_f32_e32 v160, v160
	v_exp_f32_e32 v157, v157
	v_exp_f32_e32 v161, v161
	v_exp_f32_e32 v148, v148
	v_exp_f32_e32 v158, v158
	v_exp_f32_e32 v149, v149
	v_exp_f32_e32 v159, v159
	v_add_f32_e32 v156, 1.0, v156
	v_add_f32_e32 v160, 1.0, v160
	v_add_f32_e32 v157, 1.0, v157
	v_add_f32_e32 v161, 1.0, v161
	v_add_f32_e32 v148, 1.0, v148
	v_add_f32_e32 v162, 1.0, v158
	v_add_f32_e32 v149, 1.0, v149
	v_add_f32_e32 v163, 1.0, v159
	v_rcp_f32_e32 v156, v156
	v_rcp_f32_e32 v160, v160
	v_rcp_f32_e32 v157, v157
	v_rcp_f32_e32 v161, v161
	v_rcp_f32_e32 v158, v148
	v_rcp_f32_e32 v148, v162
	v_rcp_f32_e32 v159, v149
	v_rcp_f32_e32 v149, v163

; __device__ __forceinline__ unsigned cvt_pk_bf16(float lo, float hi) { f32x2 v = {lo, hi}; bf16x2_t b = __builtin_convertvector(v, bf16x2_t); return __builtin_bit_cast(unsigned, b); }
; __device__ __forceinline__ float sigmoidf_(float x) { return __builtin_amdgcn_rcpf(1.0f + __builtin_amdgcn_exp2f(-1.4426950408889634f * x)); }
;     __device__ __forceinline__ void operator()(const Acc& acc, const Unit& u, int wr, int wc, int fr, int fq) const {
;     ...
;                 for (int bj = 0; bj < 2; ++bj) { f32x4 v0 = acc[ai][bj][m][0], v1 = acc[ai][bj][m][1];
;                     if (mode == 1) { f32x2 a = gelu_pk((f32x2){v0[0], v0[1]}), b = gelu_pk((f32x2){v0[2], v0[3]}), c = gelu_pk((f32x2){v1[0], v1[1]}), d = gelu_pk((f32x2){v1[2], v1[3]});
;                         v0 = (f32x4){a.x, a.y, b.x, b.y}; v1 = (f32x4){c.x, c.y, d.x, d.y}; }
;                     else if (mode == 2) { v0 = v0 + *(const f32x4*)(gbp + bj * HALF); v1 = v1 + *(const f32x4*)(gbp + bj * HALF + 4);
; #pragma unroll
;                         for (int i = 0; i < 4; ++i) { v0[i] = sigmoidf_(v0[i]); v1[i] = sigmoidf_(v1[i]); } }
;                     u32x4 w; w.x = cvt_pk_bf16(v0[0], v0[1]); w.y = cvt_pk_bf16(v0[2], v0[3]); w.z = cvt_pk_bf16(v1[0], v1[1]); w.w = cvt_pk_bf16(v1[2], v1[3]);
;                     *(u32x4*)(rowp + (mode == 0 ? (size_t)bj * SEQ * 128 : (size_t)bj * HALF)) = w; } }
.LBB0_281:
	v_cvt_pk_bf16_f32 v156, v156, v157
	v_cvt_pk_bf16_f32 v157, v158, v159
	v_cvt_pk_bf16_f32 v158, v160, v161
	v_cvt_pk_bf16_f32 v159, v148, v149
	s_and_b64 vcc, exec, s[48:49]
	s_mov_b64 s[18:19], -1
	global_store_dwordx4 v[146:147], v[156:159], off
	s_cbranch_vccnz .LBB0_285
	s_and_b64 vcc, exec, s[44:45]
	v_mov_b32_e32 v149, v19
	v_mov_b32_e32 v148, v18
	v_mov_b32_e32 v161, v17
	v_mov_b32_e32 v160, v16
	v_mov_b32_e32 v159, v23
	v_mov_b32_e32 v158, v22
	v_mov_b32_e32 v157, v21
	v_mov_b32_e32 v156, v20
	s_cbranch_vccnz .LBB0_284
	v_mov_b32_e32 v156, v240
	v_mov_b32_e32 v157, v241
	v_mov_b32_e32 v158, v242
	v_mov_b32_e32 v159, v243
	v_mov_b32_e32 v160, v244
	v_mov_b32_e32 v161, v245
	v_mov_b32_e32 v162, v246
	v_mov_b32_e32 v163, v247
	v_pk_add_f32 v[148:149], v[22:23], v[158:159]
	v_pk_add_f32 v[156:157], v[20:21], v[156:157]
	v_pk_add_f32 v[158:159], v[18:19], v[162:163]
	v_pk_add_f32 v[160:161], v[16:17], v[160:161]
	v_mul_f32_e32 v156, 0xbfb8aa3b, v156
	v_mul_f32_e32 v160, 0xbfb8aa3b, v160
	v_mul_f32_e32 v157, 0xbfb8aa3b, v157
	v_mul_f32_e32 v161, 0xbfb8aa3b, v161
	v_mul_f32_e32 v148, 0xbfb8aa3b, v148
	v_mul_f32_e32 v158, 0xbfb8aa3b, v158
	v_mul_f32_e32 v149, 0xbfb8aa3b, v149
	v_mul_f32_e32 v159, 0xbfb8aa3b, v159
	v_exp_f32_e32 v156, v156
	v_exp_f32_e32 v160, v160
	v_exp_f32_e32 v157, v157
	v_exp_f32_e32 v161, v161
	v_exp_f32_e32 v148, v148
	v_exp_f32_e32 v158, v158
	v_exp_f32_e32 v149, v149
	v_exp_f32_e32 v159, v159
	v_add_f32_e32 v156, 1.0, v156
	v_add_f32_e32 v160, 1.0, v160
	v_add_f32_e32 v157, 1.0, v157
	v_add_f32_e32 v161, 1.0, v161
	v_add_f32_e32 v148, 1.0, v148
	v_add_f32_e32 v162, 1.0, v158
	v_add_f32_e32 v149, 1.0, v149
	v_add_f32_e32 v163, 1.0, v159
	v_rcp_f32_e32 v156, v156
	v_rcp_f32_e32 v160, v160
	v_rcp_f32_e32 v157, v157
	v_rcp_f32_e32 v161, v161
	v_rcp_f32_e32 v158, v148
	v_rcp_f32_e32 v148, v162
	v_rcp_f32_e32 v159, v149
	v_rcp_f32_e32 v149, v163

; __device__ __forceinline__ float sigmoidf_(float x) { return __builtin_amdgcn_rcpf(1.0f + __builtin_amdgcn_exp2f(-1.4426950408889634f * x)); }
;     __device__ __forceinline__ void operator()(const Acc& acc, const Unit& u, int wr, int wc, int fr, int fq) const {
;     ...
;                 for (int bj = 0; bj < 2; ++bj) { f32x4 v0 = acc[ai][bj][m][0], v1 = acc[ai][bj][m][1];
;                     if (mode == 1) { f32x2 a = gelu_pk((f32x2){v0[0], v0[1]}), b = gelu_pk((f32x2){v0[2], v0[3]}), c = gelu_pk((f32x2){v1[0], v1[1]}), d = gelu_pk((f32x2){v1[2], v1[3]});
;                         v0 = (f32x4){a.x, a.y, b.x, b.y}; v1 = (f32x4){c.x, c.y, d.x, d.y}; }
;                     else if (mode == 2) { v0 = v0 + *(const f32x4*)(gbp + bj * HALF); v1 = v1 + *(const f32x4*)(gbp + bj * HALF + 4);
; #pragma unroll
;                         for (int i = 0; i < 4; ++i) { v0[i] = sigmoidf_(v0[i]); v1[i] = sigmoidf_(v1[i]); } }
.LBB0_290:
	s_and_b64 vcc, exec, s[44:45]
	v_mov_b32_e32 v145, v11
	v_mov_b32_e32 v144, v10
	v_mov_b32_e32 v157, v9
	v_mov_b32_e32 v156, v8
	v_mov_b32_e32 v149, v15
	v_mov_b32_e32 v148, v14
	v_mov_b32_e32 v147, v13
	v_mov_b32_e32 v146, v12
	s_cbranch_vccnz .LBB0_292
	v_mov_b32_e32 v144, v232
	v_mov_b32_e32 v145, v233
	v_mov_b32_e32 v146, v234
	v_mov_b32_e32 v147, v235
	v_mov_b32_e32 v156, v236
	v_mov_b32_e32 v157, v237
	v_mov_b32_e32 v158, v238
	v_mov_b32_e32 v159, v239
	v_pk_add_f32 v[146:147], v[14:15], v[146:147]
	v_pk_add_f32 v[144:145], v[12:13], v[144:145]
	v_pk_add_f32 v[148:149], v[10:11], v[158:159]
	v_pk_add_f32 v[156:157], v[8:9], v[156:157]
	v_mul_f32_e32 v144, 0xbfb8aa3b, v144
	v_mul_f32_e32 v156, 0xbfb8aa3b, v156
	v_mul_f32_e32 v145, 0xbfb8aa3b, v145
	v_mul_f32_e32 v157, 0xbfb8aa3b, v157
	v_mul_f32_e32 v146, 0xbfb8aa3b, v146
	v_mul_f32_e32 v148, 0xbfb8aa3b, v148
	v_mul_f32_e32 v147, 0xbfb8aa3b, v147
	v_mul_f32_e32 v149, 0xbfb8aa3b, v149
	v_exp_f32_e32 v144, v144
	v_exp_f32_e32 v156, v156
	v_exp_f32_e32 v145, v145
	v_exp_f32_e32 v157, v157
	v_exp_f32_e32 v146, v146
	v_exp_f32_e32 v148, v148
	v_exp_f32_e32 v147, v147
	v_exp_f32_e32 v149, v149
	v_add_f32_e32 v144, 1.0, v144
	v_add_f32_e32 v156, 1.0, v156
	v_add_f32_e32 v145, 1.0, v145
	v_add_f32_e32 v157, 1.0, v157
	v_add_f32_e32 v158, 1.0, v146
	v_add_f32_e32 v159, 1.0, v148
	v_add_f32_e32 v160, 1.0, v147
	v_add_f32_e32 v161, 1.0, v149
	v_rcp_f32_e32 v146, v144
	v_rcp_f32_e32 v156, v156
	v_rcp_f32_e32 v147, v145
	v_rcp_f32_e32 v157, v157
	v_rcp_f32_e32 v148, v158
	v_rcp_f32_e32 v144, v159
	v_rcp_f32_e32 v149, v160
	v_rcp_f32_e32 v145, v161

; __device__ __forceinline__ unsigned cvt_pk_bf16(float lo, float hi) { f32x2 v = {lo, hi}; bf16x2_t b = __builtin_convertvector(v, bf16x2_t); return __builtin_bit_cast(unsigned, b); }
; __device__ __forceinline__ float sigmoidf_(float x) { return __builtin_amdgcn_rcpf(1.0f + __builtin_amdgcn_exp2f(-1.4426950408889634f * x)); }
;     __device__ __forceinline__ void operator()(const Acc& acc, const Unit& u, int wr, int wc, int fr, int fq) const {
;     ...
;                 for (int bj = 0; bj < 2; ++bj) { f32x4 v0 = acc[ai][bj][m][0], v1 = acc[ai][bj][m][1];
;                     if (mode == 1) { f32x2 a = gelu_pk((f32x2){v0[0], v0[1]}), b = gelu_pk((f32x2){v0[2], v0[3]}), c = gelu_pk((f32x2){v1[0], v1[1]}), d = gelu_pk((f32x2){v1[2], v1[3]});
;                         v0 = (f32x4){a.x, a.y, b.x, b.y}; v1 = (f32x4){c.x, c.y, d.x, d.y}; }
;                     else if (mode == 2) { v0 = v0 + *(const f32x4*)(gbp + bj * HALF); v1 = v1 + *(const f32x4*)(gbp + bj * HALF + 4);
; #pragma unroll
;                         for (int i = 0; i < 4; ++i) { v0[i] = sigmoidf_(v0[i]); v1[i] = sigmoidf_(v1[i]); } }
;                     u32x4 w; w.x = cvt_pk_bf16(v0[0], v0[1]); w.y = cvt_pk_bf16(v0[2], v0[3]); w.z = cvt_pk_bf16(v1[0], v1[1]); w.w = cvt_pk_bf16(v1[2], v1[3]);
;                     *(u32x4*)(rowp + (mode == 0 ? (size_t)bj * SEQ * 128 : (size_t)bj * HALF)) = w; } }
.LBB0_295:
	v_cvt_pk_bf16_f32 v146, v146, v147
	v_cvt_pk_bf16_f32 v147, v148, v149
	v_cvt_pk_bf16_f32 v148, v156, v157
	v_cvt_pk_bf16_f32 v149, v144, v145
	s_and_b64 vcc, exec, s[48:49]
	s_mov_b64 s[18:19], -1
	global_store_dwordx4 v[142:143], v[146:149], off
	s_cbranch_vccnz .LBB0_299
	s_and_b64 vcc, exec, s[44:45]
	v_mov_b32_e32 v157, v3
	v_mov_b32_e32 v156, v2
	v_mov_b32_e32 v149, v1
	v_mov_b32_e32 v148, v0
	v_mov_b32_e32 v147, v7
	v_mov_b32_e32 v146, v6
	v_mov_b32_e32 v145, v5
	v_mov_b32_e32 v144, v4
	s_cbranch_vccnz .LBB0_298
	v_mov_b32_e32 v144, v240
	v_mov_b32_e32 v145, v241
	v_mov_b32_e32 v146, v242
	v_mov_b32_e32 v147, v243
	v_mov_b32_e32 v156, v244
	v_mov_b32_e32 v157, v245
	v_mov_b32_e32 v158, v246
	v_mov_b32_e32 v159, v247
	v_pk_add_f32 v[140:141], v[6:7], v[146:147]
	v_pk_add_f32 v[144:145], v[4:5], v[144:145]
	v_pk_add_f32 v[146:147], v[2:3], v[158:159]
	v_pk_add_f32 v[148:149], v[0:1], v[156:157]
	v_mul_f32_e32 v144, 0xbfb8aa3b, v144
	v_mul_f32_e32 v148, 0xbfb8aa3b, v148
	v_mul_f32_e32 v145, 0xbfb8aa3b, v145
	v_mul_f32_e32 v149, 0xbfb8aa3b, v149
	v_mul_f32_e32 v140, 0xbfb8aa3b, v140
	v_mul_f32_e32 v146, 0xbfb8aa3b, v146
	v_mul_f32_e32 v141, 0xbfb8aa3b, v141
	v_mul_f32_e32 v147, 0xbfb8aa3b, v147
	v_exp_f32_e32 v144, v144
	v_exp_f32_e32 v148, v148
	v_exp_f32_e32 v145, v145
	v_exp_f32_e32 v149, v149
	v_exp_f32_e32 v140, v140
	v_exp_f32_e32 v146, v146
	v_exp_f32_e32 v141, v141
	v_exp_f32_e32 v147, v147
	v_add_f32_e32 v144, 1.0, v144
	v_add_f32_e32 v148, 1.0, v148
	v_add_f32_e32 v145, 1.0, v145
	v_add_f32_e32 v149, 1.0, v149
	v_add_f32_e32 v140, 1.0, v140
	v_add_f32_e32 v156, 1.0, v146
	v_add_f32_e32 v141, 1.0, v141
	v_add_f32_e32 v157, 1.0, v147
	v_rcp_f32_e32 v144, v144
	v_rcp_f32_e32 v148, v148
	v_rcp_f32_e32 v145, v145
	v_rcp_f32_e32 v149, v149
	v_rcp_f32_e32 v146, v140
	v_rcp_f32_e32 v156, v156
	v_rcp_f32_e32 v147, v141
	v_rcp_f32_e32 v157, v157
